# prep RMSNorm loop software-pipelined: next iteration's two rows loaded into a second register set before the current rows are normalised and stored; gain loads hoisted
# baseline (speedup 1.0000x reference)
; DI int tidx() { int t = threadIdx.x; asm volatile("" : "+v"(t)); return t; }
; DI void rms_rows(const float* X, const float* g, bf16_t* out, int nrows) {
;   const int wid = tidx() >> 6, lane = tidx() & 63; const int stride = gridDim.x * 8;
;   for (int r = blockIdx.x * 8 + wid; r < nrows; r += 2 * stride) {
;     const int r2 = r + stride; const bool has2 = r2 < nrows;
;     const f32x4* xa = (const f32x4*)(X + (size_t)r * DM); const f32x4* xb = (const f32x4*)(X + (size_t)(has2 ? r2 : r) * DM);
;     f32x4 va[4], vb[4]; float sa = 0.f, sb = 0.f;
; #pragma unroll
;     for (int i = 0; i < 4; ++i) { va[i] = __builtin_nontemporal_load(xa + lane + 64 * i); vb[i] = __builtin_nontemporal_load(xb + lane + 64 * i); }
.LBB0_51:
	s_or_b64 exec, exec, s[0:1]
	s_add_u32 s44, s74, 0x4000000
	v_mov_b32_e32 v0, v212
	v_readlane_b32 s0, v254, 0
	s_addc_u32 s45, s75, 0
	s_lshl_b32 s3, s0, 3
	v_ashrrev_i32_e32 v1, 6, v0
	v_add_u32_e32 v56, s3, v1
	s_mov_b32 s13, 0x8000
	v_mov_b32_e32 v0, v212
	s_lshl_b32 s2, s90, 3
	v_cmp_gt_i32_e32 vcc, s13, v56
	v_mbcnt_lo_u32_b32 v154, -1, 0
	s_and_saveexec_b64 s[8:9], vcc
	s_cbranch_execz .LBB0_62
	v_mbcnt_hi_u32_b32 v1, -1, v154
	v_and_b32_e32 v3, 64, v1
	v_xor_b32_e32 v2, 32, v1
	v_add_u32_e32 v3, 64, v3
	v_cmp_lt_i32_e32 vcc, v2, v3
	v_and_b32_e32 v0, 63, v0
	v_lshlrev_b32_e32 v36, 4, v0
	v_cndmask_b32_e32 v2, v1, v2, vcc
	v_lshlrev_b32_e32 v43, 2, v2
	v_xor_b32_e32 v2, 16, v1
	v_cmp_lt_i32_e32 vcc, v2, v3
	v_lshlrev_b32_e32 v0, 2, v0
	v_mov_b32_e32 v37, 0
	v_cndmask_b32_e32 v2, v1, v2, vcc
	v_lshlrev_b32_e32 v45, 2, v2
	v_xor_b32_e32 v2, 8, v1
	v_cmp_lt_i32_e32 vcc, v2, v3
	v_lshlrev_b32_e32 v50, 1, v0
	v_lshl_add_u64 v[38:39], s[16:17], 0, v[36:37]
	v_cndmask_b32_e32 v2, v1, v2, vcc
	v_lshlrev_b32_e32 v47, 2, v2
	v_xor_b32_e32 v2, 4, v1
	v_cmp_lt_i32_e32 vcc, v2, v3
	v_lshl_add_u64 v[40:41], s[22:23], 0, v[36:37]
	v_or_b32_e32 v42, 0x100, v0
	v_cndmask_b32_e32 v2, v1, v2, vcc
	v_lshlrev_b32_e32 v49, 2, v2
	v_xor_b32_e32 v2, 2, v1
	v_cmp_lt_i32_e32 vcc, v2, v3
	v_or_b32_e32 v44, 0x200, v0
	v_or_b32_e32 v46, 0x300, v0
	v_cndmask_b32_e32 v2, v1, v2, vcc
	v_lshlrev_b32_e32 v64, 2, v2
	v_xor_b32_e32 v2, 1, v1
	v_cmp_lt_i32_e32 vcc, v2, v3
	s_mov_b64 s[10:11], 0
	s_mov_b32 s12, 0x3a800000
	v_cndmask_b32_e32 v1, v1, v2, vcc
	v_lshlrev_b32_e32 v65, 2, v1
	v_mov_b32_e32 v48, 0x358637bd
	s_mov_b32 s14, 0x800000
	v_mov_b32_e32 v52, v50
	v_mov_b32_e32 v53, v37
	s_movk_i32 s15, 0x7fff
	global_load_dwordx4 v[96:99], v[40:41], off
	global_load_dwordx4 v[100:103], v[40:41], off offset:1024
	global_load_dwordx4 v[104:107], v[40:41], off offset:2048
	global_load_dwordx4 v[108:111], v[40:41], off offset:3072
	v_ashrrev_i32_e32 v57, 31, v56
	v_lshlrev_b64 v[86:87], 12, v[56:57]
	v_add_u32_e32 v54, s2, v56
	v_lshl_add_u64 v[86:87], v[38:39], 0, v[86:87]
	v_cmp_gt_i32_e32 vcc, s13, v54
	global_load_dwordx4 v[88:91], v[86:87], off nt
	global_load_dwordx4 v[92:95], v[86:87], off offset:1024 nt
	global_load_dwordx4 v[112:115], v[86:87], off offset:2048 nt
	global_load_dwordx4 v[116:119], v[86:87], off offset:3072 nt
	v_cndmask_b32_e32 v84, v56, v54, vcc
	v_ashrrev_i32_e32 v85, 31, v84
	v_lshlrev_b64 v[84:85], 12, v[84:85]
	v_lshl_add_u64 v[84:85], v[38:39], 0, v[84:85]
	global_load_dwordx4 v[120:123], v[84:85], off nt
	global_load_dwordx4 v[124:127], v[84:85], off offset:1024 nt
	global_load_dwordx4 v[168:171], v[84:85], off offset:2048 nt
	global_load_dwordx4 v[172:175], v[84:85], off offset:3072 nt
	s_waitcnt vmcnt(0)
	s_branch .LBB0_54

; DI int tidx() { int t = threadIdx.x; asm volatile("" : "+v"(t)); return t; }
; DI void rms_rows(const float* X, const float* g, bf16_t* out, int nrows) {
;   const int wid = tidx() >> 6, lane = tidx() & 63; const int stride = gridDim.x * 8;
;   for (int r = blockIdx.x * 8 + wid; r < nrows; r += 2 * stride) {
;     const int r2 = r + stride; const bool has2 = r2 < nrows;
;     const f32x4* xa = (const f32x4*)(X + (size_t)r * DM); const f32x4* xb = (const f32x4*)(X + (size_t)(has2 ? r2 : r) * DM);
;     f32x4 va[4], vb[4]; float sa = 0.f, sb = 0.f;
; #pragma unroll
;     for (int i = 0; i < 4; ++i) { va[i] = __builtin_nontemporal_load(xa + lane + 64 * i); vb[i] = __builtin_nontemporal_load(xb + lane + 64 * i); }
; #pragma unroll
;     for (int i = 0; i < 4; ++i) { sa += va[i][0] * va[i][0] + va[i][1] * va[i][1] + va[i][2] * va[i][2] + va[i][3] * va[i][3]; sb += vb[i][0] * vb[i][0] + vb[i][1] * vb[i][1] + vb[i][2] * vb[i][2] + vb[i][3] * vb[i][3]; }
.LBB0_54:
	s_waitcnt vmcnt(4)
	v_mov_b32_e32 v28, v88
	v_mov_b32_e32 v29, v89
	v_mov_b32_e32 v30, v90
	v_mov_b32_e32 v31, v91
	v_mov_b32_e32 v20, v92
	v_mov_b32_e32 v21, v93
	v_mov_b32_e32 v22, v94
	v_mov_b32_e32 v23, v95
	v_mov_b32_e32 v12, v112
	v_mov_b32_e32 v13, v113
	v_mov_b32_e32 v14, v114
	v_mov_b32_e32 v15, v115
	v_mov_b32_e32 v4, v116
	v_mov_b32_e32 v5, v117
	v_mov_b32_e32 v6, v118
	v_mov_b32_e32 v7, v119
	v_mov_b32_e32 v24, v120
	v_mov_b32_e32 v25, v121
	v_mov_b32_e32 v26, v122
	v_mov_b32_e32 v27, v123
	v_mov_b32_e32 v16, v124
	v_mov_b32_e32 v17, v125
	v_mov_b32_e32 v18, v126
	v_mov_b32_e32 v19, v127
	v_mov_b32_e32 v8, v168
	v_mov_b32_e32 v9, v169
	v_mov_b32_e32 v10, v170
	v_mov_b32_e32 v11, v171
	v_mov_b32_e32 v0, v172
	v_mov_b32_e32 v1, v173
	v_mov_b32_e32 v2, v174
	v_mov_b32_e32 v3, v175
	v_ashrrev_i32_e32 v57, 31, v56
	v_add_u32_e32 v54, s2, v56
	v_cmp_gt_i32_e32 vcc, s13, v54
	v_add_u32_e32 v86, s2, v54
	v_cmp_gt_i32_e64 s[4:5], s13, v86
	s_nop 1
	s_and_b64 s[4:5], s[4:5], exec
	s_cbranch_scc0 .Lprep_nopf
	v_add_u32_e32 v84, s2, v86
	v_cmp_gt_i32_e64 s[4:5], s13, v84
	s_nop 1
	v_cndmask_b32_e64 v84, v86, v84, s[4:5]
	v_ashrrev_i32_e32 v87, 31, v86
	v_lshlrev_b64 v[86:87], 12, v[86:87]
	v_lshl_add_u64 v[86:87], v[38:39], 0, v[86:87]
	global_load_dwordx4 v[88:91], v[86:87], off nt
	global_load_dwordx4 v[92:95], v[86:87], off offset:1024 nt
	global_load_dwordx4 v[112:115], v[86:87], off offset:2048 nt
	global_load_dwordx4 v[116:119], v[86:87], off offset:3072 nt
	v_ashrrev_i32_e32 v85, 31, v84
	v_lshlrev_b64 v[84:85], 12, v[84:85]
	v_lshl_add_u64 v[84:85], v[38:39], 0, v[84:85]
	global_load_dwordx4 v[120:123], v[84:85], off nt
	global_load_dwordx4 v[124:127], v[84:85], off offset:1024 nt
	global_load_dwordx4 v[168:171], v[84:85], off offset:2048 nt
	global_load_dwordx4 v[172:175], v[84:85], off offset:3072 nt
.Lprep_nopf:
	v_lshlrev_b64 v[56:57], 11, v[56:57]
	v_ashrrev_i32_e32 v55, 31, v54
	v_mov_b32_e32 v60, v29
	v_mov_b32_e32 v61, v21
	v_mov_b32_e32 v70, v13
	v_mov_b32_e32 v71, v5
	v_mov_b32_e32 v58, v28
	v_mov_b32_e32 v59, v20
	v_mov_b32_e32 v68, v12
	v_mov_b32_e32 v69, v4
	v_pk_mul_f32 v[60:61], v[60:61], v[60:61]
	v_pk_mul_f32 v[70:71], v[70:71], v[70:71]
	v_mov_b32_e32 v62, v30
	v_mov_b32_e32 v63, v22
	v_pk_fma_f32 v[58:59], v[58:59], v[58:59], v[60:61]
	v_pk_fma_f32 v[60:61], v[68:69], v[68:69], v[70:71]
	v_mov_b32_e32 v70, v25
	v_mov_b32_e32 v71, v17
	v_mov_b32_e32 v68, v24
	v_mov_b32_e32 v69, v16
	v_mov_b32_e32 v82, v9
	v_mov_b32_e32 v83, v1
	v_pk_fma_f32 v[58:59], v[62:63], v[62:63], v[58:59]
	v_pk_mul_f32 v[62:63], v[70:71], v[70:71]
	v_mov_b32_e32 v66, v31
	v_mov_b32_e32 v67, v23
	v_mov_b32_e32 v76, v26
	v_mov_b32_e32 v77, v18
	v_mov_b32_e32 v80, v8
	v_mov_b32_e32 v81, v0
	v_pk_mul_f32 v[70:71], v[82:83], v[82:83]
	v_pk_fma_f32 v[62:63], v[68:69], v[68:69], v[62:63]
	v_mov_b32_e32 v72, v14
	v_mov_b32_e32 v73, v6
	v_mov_b32_e32 v78, v27
	v_mov_b32_e32 v79, v19
	v_mov_b32_e32 v84, v10
	v_mov_b32_e32 v85, v2
	v_pk_fma_f32 v[58:59], v[66:67], v[66:67], v[58:59]
	v_pk_fma_f32 v[66:67], v[80:81], v[80:81], v[70:71]
	v_pk_fma_f32 v[62:63], v[76:77], v[76:77], v[62:63]
	v_mov_b32_e32 v74, v15
	v_mov_b32_e32 v75, v7
	v_mov_b32_e32 v86, v11
	v_mov_b32_e32 v87, v3
	v_pk_fma_f32 v[60:61], v[72:73], v[72:73], v[60:61]
	v_pk_fma_f32 v[66:67], v[84:85], v[84:85], v[66:67]
	v_pk_fma_f32 v[62:63], v[78:79], v[78:79], v[62:63]
	v_pk_fma_f32 v[60:61], v[74:75], v[74:75], v[60:61]
	v_mov_b32_e32 v69, v58
	v_pk_fma_f32 v[66:67], v[86:87], v[86:87], v[66:67]
	v_mov_b32_e32 v68, v62
	v_mov_b32_e32 v58, v63
	v_mov_b32_e32 v71, v60
	v_mov_b32_e32 v70, v66
	v_pk_add_f32 v[58:59], v[68:69], v[58:59]
	v_mov_b32_e32 v60, v67
	v_pk_add_f32 v[58:59], v[58:59], v[70:71]
	s_nop 0
	v_pk_add_f32 v[58:59], v[58:59], v[60:61]
	ds_bpermute_b32 v61, v43, v59
	ds_bpermute_b32 v60, v43, v58
	s_waitcnt lgkmcnt(0)
	v_pk_add_f32 v[58:59], v[58:59], v[60:61]
	ds_bpermute_b32 v61, v45, v59
	ds_bpermute_b32 v60, v45, v58
	s_waitcnt lgkmcnt(0)
	v_pk_add_f32 v[58:59], v[58:59], v[60:61]
	ds_bpermute_b32 v61, v47, v59
	ds_bpermute_b32 v60, v47, v58
	s_waitcnt lgkmcnt(0)
	v_pk_add_f32 v[58:59], v[58:59], v[60:61]
	ds_bpermute_b32 v61, v49, v59
	ds_bpermute_b32 v60, v49, v58
	s_waitcnt lgkmcnt(0)
	v_pk_add_f32 v[58:59], v[58:59], v[60:61]
	ds_bpermute_b32 v61, v64, v59
	ds_bpermute_b32 v60, v64, v58
	s_waitcnt lgkmcnt(0)
	v_pk_add_f32 v[58:59], v[58:59], v[60:61]
	ds_bpermute_b32 v63, v65, v59
	ds_bpermute_b32 v62, v65, v58
	v_lshl_add_u64 v[60:61], s[44:45], 0, v[56:57]
	v_lshlrev_b64 v[56:57], 11, v[54:55]
	v_lshl_add_u64 v[66:67], v[60:61], 0, v[52:53]
	s_waitcnt lgkmcnt(0)
	v_pk_add_f32 v[58:59], v[58:59], v[62:63]
	s_nop 0
	v_pk_fma_f32 v[58:59], v[58:59], s[12:13], v[48:49] op_sel_hi:[1,0,0]
	s_nop 0
	v_mul_f32_e32 v36, 0x4b800000, v59
	v_cmp_gt_f32_e64 s[4:5], s14, v59
	v_mul_f32_e32 v51, 0x4b800000, v58
	v_cmp_gt_f32_e64 s[6:7], s14, v58
	v_cndmask_b32_e64 v36, v59, v36, s[4:5]
	v_rsq_f32_e32 v36, v36
	v_cndmask_b32_e64 v51, v58, v51, s[6:7]
	v_rsq_f32_e32 v51, v51
	v_lshl_add_u64 v[58:59], s[44:45], 0, v[56:57]
	v_mul_f32_e32 v55, 0x45800000, v36
	v_cndmask_b32_e64 v62, v36, v55, s[4:5]
	v_mul_f32_e32 v56, 0x45800000, v51
	v_pk_mul_f32 v[28:29], v[28:29], v[62:63] op_sel_hi:[1,0]
	v_pk_mul_f32 v[30:31], v[30:31], v[62:63] op_sel_hi:[1,0]
	v_cndmask_b32_e64 v56, v51, v56, s[6:7]
	v_pk_mul_f32 v[30:31], v[98:99], v[30:31]
	v_pk_mul_f32 v[28:29], v[96:97], v[28:29]
	v_mov_b32_e32 v57, v56
	v_cvt_pk_bf16_f32 v28, v28, v29
	v_cvt_pk_bf16_f32 v29, v30, v31
	global_store_dwordx2 v[66:67], v[28:29], off
	s_and_saveexec_b64 s[0:1], vcc
	s_cbranch_execz .LBB0_56
	v_mov_b32_e32 v30, v56
	v_mov_b32_e32 v31, v56
	v_pk_mul_f32 v[26:27], v[26:27], v[30:31]
	v_pk_mul_f32 v[24:25], v[24:25], v[56:57]
	v_mov_b32_e32 v51, v37
	v_pk_mul_f32 v[26:27], v[98:99], v[26:27]
	v_pk_mul_f32 v[24:25], v[96:97], v[24:25]
	v_lshl_add_u64 v[28:29], v[58:59], 0, v[50:51]
	v_cvt_pk_bf16_f32 v24, v24, v25
	v_cvt_pk_bf16_f32 v25, v26, v27
	global_store_dwordx2 v[28:29], v[24:25], off
